# out and ple-gate K loops: fragment reads ordered by first use with counted lgkmcnt waits
# speedup vs baseline: 1.0178x; 1.0029x over previous
; #define LASP __attribute__((address_space(3)))
; DI void gemm_dma(f32x4 (&acc)[4][4], const bf16_t* Ap, int lda, const bf16_t* Bp, int ldb, int K, char* lds) {
;     ...
;   auto issue = [&](int kt) {
;     char* sb = lds + (kt & 1) * 32768 + wave * 4096;
; #pragma unroll
;     for (int i = 0; i < 4; ++i) {
;       __builtin_amdgcn_global_load_lds((const unsigned*)(ga[i] + kt * 64), (LASP unsigned*)(sb + i * 1024), 16, 0, 0);
;       __builtin_amdgcn_global_load_lds((const unsigned*)(gb[i] + kt * 64), (LASP unsigned*)(sb + 16384 + i * 1024), 16, 0, 0);
;     }
;   };
;   const int sw = l15 & 7;
;   const unsigned lbase = (unsigned)(size_t)(LASP char*)lds;
;   const unsigned a0 = (unsigned)((wm * 64 + l15) * 128 + ((quad ^ sw) * 16)), a1 = (unsigned)((wm * 64 + l15) * 128 + (((4 + quad) ^ sw) * 16));
;   const unsigned b0 = 16384u + (unsigned)((wn * 64 + l15) * 128 + ((quad ^ sw) * 16)), b1 = 16384u + (unsigned)((wn * 64 + l15) * 128 + (((4 + quad) ^ sw) * 16));
;   asm volatile("s_waitcnt vmcnt(0)" ::: "memory");
;   __builtin_amdgcn_s_barrier();
;   asm volatile("" ::: "memory");
;   issue(0);
;   for (int kt = 0; kt < nk; ++kt) {
;     asm volatile("s_waitcnt vmcnt(0)" ::: "memory");
;     __builtin_amdgcn_s_barrier();
;     asm volatile("" ::: "memory");
;     if (kt + 1 < nk) issue(kt + 1);
;     const unsigned sa = lbase + (unsigned)((kt & 1) * 32768);
;     bf16x8 af[4], bfr[4], ag[4], bg[4];
;     asm volatile("ds_read_b128 %0, %8\n\tds_read_b128 %1, %8 offset:2048\n\tds_read_b128 %2, %8 offset:4096\n\tds_read_b128 %3, %8 offset:6144\n\t"
;                  "ds_read_b128 %4, %9\n\tds_read_b128 %5, %9 offset:2048\n\tds_read_b128 %6, %9 offset:4096\n\tds_read_b128 %7, %9 offset:6144"
;                  : "=&v"(af[0]), "=&v"(af[1]), "=&v"(af[2]), "=&v"(af[3]), "=&v"(bfr[0]), "=&v"(bfr[1]), "=&v"(bfr[2]), "=&v"(bfr[3])
;                  : "v"(sa + a0), "v"(sa + b0) : "memory");
;     asm volatile("ds_read_b128 %0, %16\n\tds_read_b128 %1, %16 offset:2048\n\tds_read_b128 %2, %16 offset:4096\n\tds_read_b128 %3, %16 offset:6144\n\t"
;                  "ds_read_b128 %4, %17\n\tds_read_b128 %5, %17 offset:2048\n\tds_read_b128 %6, %17 offset:4096\n\tds_read_b128 %7, %17 offset:6144\n\t"
;                  "s_waitcnt lgkmcnt(8)"
;                  : "=&v"(ag[0]), "=&v"(ag[1]), "=&v"(ag[2]), "=&v"(ag[3]), "=&v"(bg[0]), "=&v"(bg[1]), "=&v"(bg[2]), "=&v"(bg[3]),
.LBB0_785:
	s_add_i32 s27, s25, 0x8000
	s_and_b32 s25, s25, 0x8000
	s_and_b32 s38, s27, 0x8000
	v_add_u32_e32 v0, s25, v84
	v_or_b32_e32 v120, s25, v87
	v_add_u32_e32 v139, s25, v85
	v_add_u32_e32 v156, s25, v86
	s_add_i32 s25, s21, s38
	s_waitcnt vmcnt(0)
	s_barrier
	v_lshl_add_u64 v[88:89], v[66:67], 0, s[30:31]
	s_add_i32 s38, s25, 0x4000
	s_mov_b32 m0, s25
	v_lshl_add_u64 v[90:91], v[68:69], 0, s[30:31]
	global_load_lds_dwordx4 v[88:89], off
	s_mov_b32 m0, s38
	v_lshl_add_u64 v[92:93], v[70:71], 0, s[30:31]
	global_load_lds_dwordx4 v[90:91], off
	s_add_i32 m0, s25, 0x400
	v_lshl_add_u64 v[94:95], v[72:73], 0, s[30:31]
	global_load_lds_dwordx4 v[92:93], off
	s_add_i32 m0, s25, 0x4400
	v_lshl_add_u64 v[96:97], v[74:75], 0, s[30:31]
	global_load_lds_dwordx4 v[94:95], off
	s_add_i32 m0, s25, 0x800
	v_lshl_add_u64 v[98:99], v[76:77], 0, s[30:31]
	global_load_lds_dwordx4 v[96:97], off
	s_add_i32 m0, s25, 0x4800
	v_lshl_add_u64 v[100:101], v[78:79], 0, s[30:31]
	global_load_lds_dwordx4 v[98:99], off
	s_add_i32 m0, s25, 0xc00
	v_lshl_add_u64 v[102:103], v[80:81], 0, s[30:31]
	global_load_lds_dwordx4 v[100:101], off
	s_add_i32 m0, s25, 0x4c00
	s_add_u32 s30, s30, 0x80
	global_load_lds_dwordx4 v[102:103], off
	ds_read_b128 v[88:91], v0
	ds_read_b128 v[104:107], v120
	ds_read_b128 v[108:111], v120 offset:2048
	ds_read_b128 v[112:115], v120 offset:4096
	ds_read_b128 v[116:119], v120 offset:6144
	ds_read_b128 v[92:95], v0 offset:2048
	ds_read_b128 v[96:99], v0 offset:4096
	ds_read_b128 v[100:103], v0 offset:6144
	ds_read_b128 v[120:123], v139
	ds_read_b128 v[140:143], v156
	ds_read_b128 v[144:147], v156 offset:2048
	ds_read_b128 v[148:151], v156 offset:4096
	ds_read_b128 v[152:155], v156 offset:6144
	ds_read_b128 v[124:127], v139 offset:2048
	ds_read_b128 v[128:131], v139 offset:4096
	ds_read_b128 v[132:135], v139 offset:6144
	s_addc_u32 s31, s31, 0
	s_cmpk_lg_i32 s30, 0x780
	s_waitcnt lgkmcnt(14)
	v_mfma_f32_16x16x32_bf16 v[62:65], v[104:107], v[88:91], v[62:65]
	s_mov_b32 s25, s27
	s_waitcnt lgkmcnt(13)
	v_mfma_f32_16x16x32_bf16 v[58:61], v[108:111], v[88:91], v[58:61]
	s_waitcnt lgkmcnt(12)
	v_mfma_f32_16x16x32_bf16 v[54:57], v[112:115], v[88:91], v[54:57]
	s_waitcnt lgkmcnt(11)
	v_mfma_f32_16x16x32_bf16 v[46:49], v[116:119], v[88:91], v[46:49]
	s_waitcnt lgkmcnt(10)
	v_mfma_f32_16x16x32_bf16 v[42:45], v[104:107], v[92:95], v[42:45]
	v_mfma_f32_16x16x32_bf16 v[38:41], v[108:111], v[92:95], v[38:41]
	v_mfma_f32_16x16x32_bf16 v[34:37], v[112:115], v[92:95], v[34:37]
	v_mfma_f32_16x16x32_bf16 v[30:33], v[116:119], v[92:95], v[30:33]
	s_waitcnt lgkmcnt(9)
	v_mfma_f32_16x16x32_bf16 v[26:29], v[104:107], v[96:99], v[26:29]
	v_mfma_f32_16x16x32_bf16 v[22:25], v[108:111], v[96:99], v[22:25]
	v_mfma_f32_16x16x32_bf16 v[18:21], v[112:115], v[96:99], v[18:21]
	v_mfma_f32_16x16x32_bf16 v[14:17], v[116:119], v[96:99], v[14:17]
	s_waitcnt lgkmcnt(8)
	v_mfma_f32_16x16x32_bf16 v[10:13], v[104:107], v[100:103], v[10:13]
	v_mfma_f32_16x16x32_bf16 v[6:9], v[108:111], v[100:103], v[6:9]
	v_mfma_f32_16x16x32_bf16 v[2:5], v[112:115], v[100:103], v[2:5]
	v_mfma_f32_16x16x32_bf16 v[50:53], v[116:119], v[100:103], v[50:53]
	s_waitcnt lgkmcnt(6)
	v_mfma_f32_16x16x32_bf16 v[62:65], v[140:143], v[120:123], v[62:65]
	s_waitcnt lgkmcnt(5)
	v_mfma_f32_16x16x32_bf16 v[58:61], v[144:147], v[120:123], v[58:61]
	s_waitcnt lgkmcnt(4)
	v_mfma_f32_16x16x32_bf16 v[54:57], v[148:151], v[120:123], v[54:57]
	s_waitcnt lgkmcnt(3)
	v_mfma_f32_16x16x32_bf16 v[46:49], v[152:155], v[120:123], v[46:49]
	s_waitcnt lgkmcnt(2)
	v_mfma_f32_16x16x32_bf16 v[42:45], v[140:143], v[124:127], v[42:45]
	v_mfma_f32_16x16x32_bf16 v[38:41], v[144:147], v[124:127], v[38:41]
	v_mfma_f32_16x16x32_bf16 v[34:37], v[148:151], v[124:127], v[34:37]
	v_mfma_f32_16x16x32_bf16 v[30:33], v[152:155], v[124:127], v[30:33]
	s_waitcnt lgkmcnt(1)
	v_mfma_f32_16x16x32_bf16 v[26:29], v[140:143], v[128:131], v[26:29]
	v_mfma_f32_16x16x32_bf16 v[22:25], v[144:147], v[128:131], v[22:25]
	v_mfma_f32_16x16x32_bf16 v[18:21], v[148:151], v[128:131], v[18:21]
	v_mfma_f32_16x16x32_bf16 v[14:17], v[152:155], v[128:131], v[14:17]
	s_waitcnt lgkmcnt(0)
	v_mfma_f32_16x16x32_bf16 v[10:13], v[140:143], v[132:135], v[10:13]
	v_mfma_f32_16x16x32_bf16 v[6:9], v[144:147], v[132:135], v[6:9]
	v_mfma_f32_16x16x32_bf16 v[2:5], v[148:151], v[132:135], v[2:5]
	v_mfma_f32_16x16x32_bf16 v[50:53], v[152:155], v[132:135], v[50:53]
	s_cbranch_scc1 .LBB0_785
; DI void gemm_dma(f32x4 (&acc)[4][4], const bf16_t* Ap, int lda, const bf16_t* Bp, int ldb, int K, char* lds) {
;     ...
;   for (int kt = 0; kt < nk; ++kt) {
;     asm volatile("s_waitcnt vmcnt(0)" ::: "memory");
;     __builtin_amdgcn_s_barrier();
;     asm volatile("" ::: "memory");
;     if (kt + 1 < nk) issue(kt + 1);
;     const unsigned sa = lbase + (unsigned)((kt & 1) * 32768);
;     bf16x8 af[4], bfr[4], ag[4], bg[4];
;     asm volatile("ds_read_b128 %0, %8\n\tds_read_b128 %1, %8 offset:2048\n\tds_read_b128 %2, %8 offset:4096\n\tds_read_b128 %3, %8 offset:6144\n\t"
;                  "ds_read_b128 %4, %9\n\tds_read_b128 %5, %9 offset:2048\n\tds_read_b128 %6, %9 offset:4096\n\tds_read_b128 %7, %9 offset:6144"
;                  : "=&v"(af[0]), "=&v"(af[1]), "=&v"(af[2]), "=&v"(af[3]), "=&v"(bfr[0]), "=&v"(bfr[1]), "=&v"(bfr[2]), "=&v"(bfr[3])
;                  : "v"(sa + a0), "v"(sa + b0) : "memory");
;     asm volatile("ds_read_b128 %0, %16\n\tds_read_b128 %1, %16 offset:2048\n\tds_read_b128 %2, %16 offset:4096\n\tds_read_b128 %3, %16 offset:6144\n\t"
;                  "ds_read_b128 %4, %17\n\tds_read_b128 %5, %17 offset:2048\n\tds_read_b128 %6, %17 offset:4096\n\tds_read_b128 %7, %17 offset:6144\n\t"
;                  "s_waitcnt lgkmcnt(8)"
;                  : "=&v"(ag[0]), "=&v"(ag[1]), "=&v"(ag[2]), "=&v"(ag[3]), "=&v"(bg[0]), "=&v"(bg[1]), "=&v"(bg[2]), "=&v"(bg[3]),
;                    "+v"(af[0]), "+v"(af[1]), "+v"(af[2]), "+v"(af[3]), "+v"(bfr[0]), "+v"(bfr[1]), "+v"(bfr[2]), "+v"(bfr[3])
;                  : "v"(sa + a1), "v"(sa + b1) : "memory");
; #pragma unroll
;     for (int mi = 0; mi < 4; ++mi)
; #pragma unroll
;       for (int ni = 0; ni < 4; ++ni) acc[mi][ni] = __builtin_amdgcn_mfma_f32_16x16x32_bf16(bfr[ni], af[mi], acc[mi][ni], 0, 0, 0);
;     asm volatile("s_waitcnt lgkmcnt(0)" : "+v"(ag[0]), "+v"(ag[1]), "+v"(ag[2]), "+v"(ag[3]), "+v"(bg[0]), "+v"(bg[1]), "+v"(bg[2]), "+v"(bg[3]) :: "memory");
; #pragma unroll
;     for (int mi = 0; mi < 4; ++mi)
; #pragma unroll
;       for (int ni = 0; ni < 4; ++ni) acc[mi][ni] = __builtin_amdgcn_mfma_f32_16x16x32_bf16(bg[ni], ag[mi], acc[mi][ni], 0, 0, 0);
;   }
;   asm volatile("" ::: "memory");
;   __builtin_amdgcn_s_barrier();
;   asm volatile("" ::: "memory");
	s_waitcnt vmcnt(0)
	s_barrier
	v_add_u32_e32 v0, 0x8000, v84
	v_or_b32_e32 v84, 0x8000, v87
	ds_read_b128 v[66:69], v0
	ds_read_b128 v[70:73], v0 offset:2048
	ds_read_b128 v[74:77], v0 offset:4096
	ds_read_b128 v[78:81], v0 offset:6144
	ds_read_b128 v[88:91], v84
	ds_read_b128 v[92:95], v84 offset:2048
	ds_read_b128 v[96:99], v84 offset:4096
	ds_read_b128 v[100:103], v84 offset:6144
	v_add_u32_e32 v0, 0x8000, v85
	v_add_u32_e32 v132, 0x8000, v86
	ds_read_b128 v[84:87], v0
	ds_read_b128 v[104:107], v0 offset:2048
	ds_read_b128 v[108:111], v0 offset:4096
	ds_read_b128 v[112:115], v0 offset:6144
	ds_read_b128 v[116:119], v132
	ds_read_b128 v[120:123], v132 offset:2048
	ds_read_b128 v[124:127], v132 offset:4096
	ds_read_b128 v[128:131], v132 offset:6144
	s_waitcnt lgkmcnt(8)
	s_and_b64 vcc, exec, s[2:3]
	v_mfma_f32_16x16x32_bf16 v[62:65], v[88:91], v[66:69], v[62:65]
	s_waitcnt lgkmcnt(0)
	s_barrier
	v_mfma_f32_16x16x32_bf16 v[58:61], v[92:95], v[66:69], v[58:61]
	v_mfma_f32_16x16x32_bf16 v[54:57], v[96:99], v[66:69], v[54:57]
	v_mfma_f32_16x16x32_bf16 v[46:49], v[100:103], v[66:69], v[46:49]
	v_lshl_add_u32 v68, s26, 7, v82
	v_mfma_f32_16x16x32_bf16 v[42:45], v[88:91], v[70:73], v[42:45]
	v_mfma_f32_16x16x32_bf16 v[38:41], v[92:95], v[70:73], v[38:41]
	v_mfma_f32_16x16x32_bf16 v[34:37], v[96:99], v[70:73], v[34:37]
	v_mfma_f32_16x16x32_bf16 v[30:33], v[100:103], v[70:73], v[30:33]
	v_mfma_f32_16x16x32_bf16 v[26:29], v[88:91], v[74:77], v[26:29]
	v_mfma_f32_16x16x32_bf16 v[22:25], v[92:95], v[74:77], v[22:25]
	v_mfma_f32_16x16x32_bf16 v[18:21], v[96:99], v[74:77], v[18:21]
	v_mfma_f32_16x16x32_bf16 v[14:17], v[100:103], v[74:77], v[14:17]
	v_mfma_f32_16x16x32_bf16 v[10:13], v[88:91], v[78:81], v[10:13]
	v_mfma_f32_16x16x32_bf16 v[6:9], v[92:95], v[78:81], v[6:9]
	v_mfma_f32_16x16x32_bf16 v[2:5], v[96:99], v[78:81], v[2:5]
	v_mfma_f32_16x16x32_bf16 v[70:73], v[100:103], v[78:81], v[50:53]
	v_mfma_f32_16x16x32_bf16 v[62:65], v[116:119], v[84:87], v[62:65]
	v_mfma_f32_16x16x32_bf16 v[58:61], v[120:123], v[84:87], v[58:61]
	v_mfma_f32_16x16x32_bf16 v[54:57], v[124:127], v[84:87], v[54:57]
	v_mfma_f32_16x16x32_bf16 v[50:53], v[128:131], v[84:87], v[46:49]
	v_mfma_f32_16x16x32_bf16 v[46:49], v[116:119], v[104:107], v[42:45]
	v_mfma_f32_16x16x32_bf16 v[42:45], v[120:123], v[104:107], v[38:41]
	v_mfma_f32_16x16x32_bf16 v[38:41], v[124:127], v[104:107], v[34:37]
	v_mfma_f32_16x16x32_bf16 v[34:37], v[128:131], v[104:107], v[30:33]
	v_mfma_f32_16x16x32_bf16 v[30:33], v[116:119], v[108:111], v[26:29]
	v_mfma_f32_16x16x32_bf16 v[26:29], v[120:123], v[108:111], v[22:25]
	v_mfma_f32_16x16x32_bf16 v[22:25], v[124:127], v[108:111], v[18:21]
	v_mfma_f32_16x16x32_bf16 v[18:21], v[128:131], v[108:111], v[14:17]
	v_mfma_f32_16x16x32_bf16 v[14:17], v[116:119], v[112:115], v[10:13]
	v_mfma_f32_16x16x32_bf16 v[10:13], v[120:123], v[112:115], v[6:9]
	v_mfma_f32_16x16x32_bf16 v[6:9], v[124:127], v[112:115], v[2:5]
	v_mfma_f32_16x16x32_bf16 v[2:5], v[128:131], v[112:115], v[70:73]
	s_cbranch_vccz .LBB0_788
	v_ashrrev_i32_e32 v69, 31, v68
	s_mov_b64 s[26:27], 0
	s_branch .LBB0_789

; DI void gemm_dma(f32x4 (&acc)[4][4], const bf16_t* Ap, int lda, const bf16_t* Bp, int ldb, int K, char* lds) {
;     ...
;   for (int kt = 0; kt < nk; ++kt) {
;     asm volatile("s_waitcnt vmcnt(0)" ::: "memory");
;     __builtin_amdgcn_s_barrier();
;     asm volatile("" ::: "memory");
;     if (kt + 1 < nk) issue(kt + 1);
;     const unsigned sa = lbase + (unsigned)((kt & 1) * 32768);
;     bf16x8 af[4], bfr[4], ag[4], bg[4];
;     asm volatile("ds_read_b128 %0, %8\n\tds_read_b128 %1, %8 offset:2048\n\tds_read_b128 %2, %8 offset:4096\n\tds_read_b128 %3, %8 offset:6144\n\t"
;                  "ds_read_b128 %4, %9\n\tds_read_b128 %5, %9 offset:2048\n\tds_read_b128 %6, %9 offset:4096\n\tds_read_b128 %7, %9 offset:6144"
;                  : "=&v"(af[0]), "=&v"(af[1]), "=&v"(af[2]), "=&v"(af[3]), "=&v"(bfr[0]), "=&v"(bfr[1]), "=&v"(bfr[2]), "=&v"(bfr[3])
;                  : "v"(sa + a0), "v"(sa + b0) : "memory");
;     asm volatile("ds_read_b128 %0, %16\n\tds_read_b128 %1, %16 offset:2048\n\tds_read_b128 %2, %16 offset:4096\n\tds_read_b128 %3, %16 offset:6144\n\t"
;                  "ds_read_b128 %4, %17\n\tds_read_b128 %5, %17 offset:2048\n\tds_read_b128 %6, %17 offset:4096\n\tds_read_b128 %7, %17 offset:6144\n\t"
;                  "s_waitcnt lgkmcnt(8)"
;                  : "=&v"(ag[0]), "=&v"(ag[1]), "=&v"(ag[2]), "=&v"(ag[3]), "=&v"(bg[0]), "=&v"(bg[1]), "=&v"(bg[2]), "=&v"(bg[3]),
;                    "+v"(af[0]), "+v"(af[1]), "+v"(af[2]), "+v"(af[3]), "+v"(bfr[0]), "+v"(bfr[1]), "+v"(bfr[2]), "+v"(bfr[3])
;                  : "v"(sa + a1), "v"(sa + b1) : "memory");
; #pragma unroll
;     for (int mi = 0; mi < 4; ++mi)
; #pragma unroll
;       for (int ni = 0; ni < 4; ++ni) acc[mi][ni] = __builtin_amdgcn_mfma_f32_16x16x32_bf16(bfr[ni], af[mi], acc[mi][ni], 0, 0, 0);
;     asm volatile("s_waitcnt lgkmcnt(0)" : "+v"(ag[0]), "+v"(ag[1]), "+v"(ag[2]), "+v"(ag[3]), "+v"(bg[0]), "+v"(bg[1]), "+v"(bg[2]), "+v"(bg[3]) :: "memory");
; #pragma unroll
;     for (int mi = 0; mi < 4; ++mi)
; #pragma unroll
;       for (int ni = 0; ni < 4; ++ni) acc[mi][ni] = __builtin_amdgcn_mfma_f32_16x16x32_bf16(bg[ni], ag[mi], acc[mi][ni], 0, 0, 0);
;   }
; DI void phase_ple(const Params& p, int l, char* lds) {
;     ...
;     gemm_dma(a1, p.o_r + (size_t)mt * 128 * DM, DM, p.wt_gate + (size_t)nt * 128 * DM, DM, DM, lds);
;     u32x2 pk[4][4];
; #pragma unroll
;     for (int mi = 0; mi < 4; ++mi) {
.LBB0_903:
	s_add_i32 s40, s27, 0x8000
	s_and_b32 s27, s27, 0x8000
	s_and_b32 s41, s40, 0x8000
	v_add_u32_e32 v0, s27, v82
	v_or_b32_e32 v118, s27, v85
	v_add_u32_e32 v134, s27, v83
	v_add_u32_e32 v135, s27, v84
	s_add_i32 s27, s21, s41
	s_waitcnt vmcnt(0)
	s_barrier
	v_lshl_add_u64 v[86:87], v[66:67], 0, s[30:31]
	s_add_i32 s41, s27, 0x4000
	s_mov_b32 m0, s27
	v_lshl_add_u64 v[88:89], v[68:69], 0, s[30:31]
	global_load_lds_dwordx4 v[86:87], off
	s_mov_b32 m0, s41
	v_lshl_add_u64 v[90:91], v[70:71], 0, s[30:31]
	global_load_lds_dwordx4 v[88:89], off
	s_add_i32 m0, s27, 0x400
	v_lshl_add_u64 v[92:93], v[72:73], 0, s[30:31]
	global_load_lds_dwordx4 v[90:91], off
	s_add_i32 m0, s27, 0x4400
	v_lshl_add_u64 v[94:95], v[74:75], 0, s[30:31]
	global_load_lds_dwordx4 v[92:93], off
	s_add_i32 m0, s27, 0x800
	v_lshl_add_u64 v[96:97], v[76:77], 0, s[30:31]
	global_load_lds_dwordx4 v[94:95], off
	s_add_i32 m0, s27, 0x4800
	v_lshl_add_u64 v[98:99], v[78:79], 0, s[30:31]
	global_load_lds_dwordx4 v[96:97], off
	s_add_i32 m0, s27, 0xc00
	v_lshl_add_u64 v[100:101], v[80:81], 0, s[30:31]
	global_load_lds_dwordx4 v[98:99], off
	s_add_i32 m0, s27, 0x4c00
	s_add_u32 s30, s30, 0x80
	global_load_lds_dwordx4 v[100:101], off
	ds_read_b128 v[86:89], v0
	ds_read_b128 v[102:105], v118
	ds_read_b128 v[106:109], v118 offset:2048
	ds_read_b128 v[110:113], v118 offset:4096
	ds_read_b128 v[114:117], v118 offset:6144
	ds_read_b128 v[90:93], v0 offset:2048
	ds_read_b128 v[94:97], v0 offset:4096
	ds_read_b128 v[98:101], v0 offset:6144
	ds_read_b128 v[118:121], v134
	ds_read_b128 v[142:145], v135
	ds_read_b128 v[146:149], v135 offset:2048
	ds_read_b128 v[150:153], v135 offset:4096
	ds_read_b128 v[154:157], v135 offset:6144
	ds_read_b128 v[122:125], v134 offset:2048
	ds_read_b128 v[126:129], v134 offset:4096
	ds_read_b128 v[130:133], v134 offset:6144
	s_addc_u32 s31, s31, 0
	s_cmpk_lg_i32 s30, 0x780
	s_waitcnt lgkmcnt(14)
	v_mfma_f32_16x16x32_bf16 v[62:65], v[102:105], v[86:89], v[62:65]
	s_mov_b32 s27, s40
	s_waitcnt lgkmcnt(13)
	v_mfma_f32_16x16x32_bf16 v[58:61], v[106:109], v[86:89], v[58:61]
	s_waitcnt lgkmcnt(12)
	v_mfma_f32_16x16x32_bf16 v[54:57], v[110:113], v[86:89], v[54:57]
	s_waitcnt lgkmcnt(11)
	v_mfma_f32_16x16x32_bf16 v[46:49], v[114:117], v[86:89], v[46:49]
	s_waitcnt lgkmcnt(10)
	v_mfma_f32_16x16x32_bf16 v[42:45], v[102:105], v[90:93], v[42:45]
	v_mfma_f32_16x16x32_bf16 v[38:41], v[106:109], v[90:93], v[38:41]
	v_mfma_f32_16x16x32_bf16 v[34:37], v[110:113], v[90:93], v[34:37]
	v_mfma_f32_16x16x32_bf16 v[30:33], v[114:117], v[90:93], v[30:33]
	s_waitcnt lgkmcnt(9)
	v_mfma_f32_16x16x32_bf16 v[26:29], v[102:105], v[94:97], v[26:29]
	v_mfma_f32_16x16x32_bf16 v[22:25], v[106:109], v[94:97], v[22:25]
	v_mfma_f32_16x16x32_bf16 v[18:21], v[110:113], v[94:97], v[18:21]
	v_mfma_f32_16x16x32_bf16 v[14:17], v[114:117], v[94:97], v[14:17]
	s_waitcnt lgkmcnt(8)
	v_mfma_f32_16x16x32_bf16 v[10:13], v[102:105], v[98:101], v[10:13]
	v_mfma_f32_16x16x32_bf16 v[6:9], v[106:109], v[98:101], v[6:9]
	v_mfma_f32_16x16x32_bf16 v[2:5], v[110:113], v[98:101], v[2:5]
	v_mfma_f32_16x16x32_bf16 v[50:53], v[114:117], v[98:101], v[50:53]
	s_waitcnt lgkmcnt(6)
	v_mfma_f32_16x16x32_bf16 v[62:65], v[142:145], v[118:121], v[62:65]
	s_waitcnt lgkmcnt(5)
	v_mfma_f32_16x16x32_bf16 v[58:61], v[146:149], v[118:121], v[58:61]
	s_waitcnt lgkmcnt(4)
	v_mfma_f32_16x16x32_bf16 v[54:57], v[150:153], v[118:121], v[54:57]
	s_waitcnt lgkmcnt(3)
	v_mfma_f32_16x16x32_bf16 v[46:49], v[154:157], v[118:121], v[46:49]
	s_waitcnt lgkmcnt(2)
	v_mfma_f32_16x16x32_bf16 v[42:45], v[142:145], v[122:125], v[42:45]
	v_mfma_f32_16x16x32_bf16 v[38:41], v[146:149], v[122:125], v[38:41]
	v_mfma_f32_16x16x32_bf16 v[34:37], v[150:153], v[122:125], v[34:37]
	v_mfma_f32_16x16x32_bf16 v[30:33], v[154:157], v[122:125], v[30:33]
	s_waitcnt lgkmcnt(1)
	v_mfma_f32_16x16x32_bf16 v[26:29], v[142:145], v[126:129], v[26:29]
	v_mfma_f32_16x16x32_bf16 v[22:25], v[146:149], v[126:129], v[22:25]
	v_mfma_f32_16x16x32_bf16 v[18:21], v[150:153], v[126:129], v[18:21]
	v_mfma_f32_16x16x32_bf16 v[14:17], v[154:157], v[126:129], v[14:17]
	s_waitcnt lgkmcnt(0)
	v_mfma_f32_16x16x32_bf16 v[10:13], v[142:145], v[130:133], v[10:13]
	v_mfma_f32_16x16x32_bf16 v[6:9], v[146:149], v[130:133], v[6:9]
	v_mfma_f32_16x16x32_bf16 v[2:5], v[150:153], v[130:133], v[2:5]
	v_mfma_f32_16x16x32_bf16 v[50:53], v[154:157], v[130:133], v[50:53]
	s_cbranch_scc1 .LBB0_903
	s_waitcnt vmcnt(0)
	s_barrier
	v_add_u32_e32 v0, 0x8000, v82
	v_or_b32_e32 v74, 0x8000, v85
	ds_read_b128 v[66:69], v0
	ds_read_b128 v[70:73], v0 offset:2048
	ds_read_b128 v[78:81], v0 offset:4096
	ds_read_b128 v[86:89], v0 offset:6144
	ds_read_b128 v[90:93], v74
	ds_read_b128 v[94:97], v74 offset:2048
	ds_read_b128 v[98:101], v74 offset:4096
	ds_read_b128 v[102:105], v74 offset:6144
	s_lshl_b32 s21, s26, 7
	v_add_u32_e32 v0, 0x8000, v83
	v_add_u32_e32 v126, 0x8000, v84
	ds_read_b128 v[106:109], v0
	ds_read_b128 v[110:113], v0 offset:2048
	ds_read_b128 v[114:117], v0 offset:4096
	ds_read_b128 v[74:77], v0 offset:6144
	ds_read_b128 v[118:121], v126
	ds_read_b128 v[122:125], v126 offset:2048
	ds_read_b128 v[128:131], v126 offset:4096
	ds_read_b128 v[82:85], v126 offset:6144
	s_waitcnt lgkmcnt(8)
	s_add_i32 s30, s21, 0xffffc000
	v_mfma_f32_16x16x32_bf16 v[38:41], v[94:97], v[70:73], v[38:41]
	s_ashr_i32 s27, s21, 31
	s_cmpk_lt_i32 s26, 0x80
	v_add_u32_e32 v126, s21, v139
	v_mfma_f32_16x16x32_bf16 v[22:25], v[94:97], v[78:81], v[22:25]
	v_readlane_b32 s40, v254, 52
	s_cselect_b32 s27, s27, 0
	s_cselect_b32 s26, s21, s30
	v_mfma_f32_16x16x32_bf16 v[14:17], v[102:105], v[78:81], v[14:17]
	s_waitcnt lgkmcnt(0)
	v_ashrrev_i32_e32 v127, 31, v126
	v_readlane_b32 s42, v254, 54
	v_mfma_f32_16x16x32_bf16 v[10:13], v[90:93], v[86:89], v[10:13]
	v_readlane_b32 s43, v254, 55
	s_cselect_b32 s21, s20, s22
	s_cselect_b32 s30, s23, s39
	v_mfma_f32_16x16x32_bf16 v[6:9], v[94:97], v[86:89], v[6:9]
	s_lshl_b64 s[26:27], s[26:27], 10
	s_barrier
; DI unsigned pk2(float a, float b) { f32x2 v = {a, b}; bfv2 r = __builtin_convertvector(v, bfv2); return __builtin_bit_cast(unsigned, r); }
; DI float sigmoidf_(float x) { return __builtin_amdgcn_rcpf(1.0f + __expf(-x)); }
; template <bool A_F32>
; DI void gemm_core(f32x4 (&acc)[4][4], const void* Ap, int lda, const bf16_t* Bp, int ldb, int K, char* lds) {
;     ...
;   auto gload = [&](int kt) {
; #pragma unroll
;     for (int i = 0; i < 4; ++i) {
;       const int c = tid + 256 * i; const int row = c >> 3, c8 = (c & 7) * 8;
;       if (!A_F32) ra[i] = *(const u32x4*)((const bf16_t*)Ap + (size_t)row * lda + kt * 64 + c8);
;       rb[i] = *(const u32x4*)(Bp + (size_t)row * ldb + kt * 64 + c8);
;     }
;   };
;   auto sstore = [&](int buf, int kt) {
; #pragma unroll
;     for (int i = 0; i < 4; ++i) {
;       const int c = tid + 256 * i; const int row = c >> 3, c8 = (c & 7) * 8;
;       if (A_F32) {
;         const float* a = (const float*)Ap + (size_t)row * lda + kt * 64 + c8;
;         const f32x4 v0 = *(const f32x4*)a, v1 = *(const f32x4*)(a + 4);
;         u32x4 t; t[0] = pk2(v0[0], v0[1]); t[1] = pk2(v0[2], v0[3]); t[2] = pk2(v1[0], v1[1]); t[3] = pk2(v1[2], v1[3]);
;         *(u32x4*)(As + (buf * 128 + row) * GLD + c8) = t;
;       } else {
;         *(u32x4*)(As + (buf * 128 + row) * GLD + c8) = ra[i];
;       }
;       *(u32x4*)(Bs + (buf * 128 + row) * GLD + c8) = rb[i];
;     }
;   };
;   gload(0); sstore(0, 0); __syncthreads();
; DI void phase_ple(const Params& p, int l, char* lds) {
;     ...
;       const float rs = rsqrtf(p.ss2[mt * 128 + wm * 64 + mi * 16 + l15] * (1.0f / 1024.0f) + 1e-6f);
; #pragma unroll
;       for (int ni = 0; ni < 4; ++ni) { const f32x4 v = a1[mi][ni] * rs; pk[mi][ni][0] = pk2(sigmoidf_(v[0]), sigmoidf_(v[1])); pk[mi][ni][1] = pk2(sigmoidf_(v[2]), sigmoidf_(v[3])); }
;     }
;     zero_acc(a1);
;     const int r0 = mt * 128;
;     const float* pa = r0 < MP ? p.pp + ((size_t)l * MP + r0) * 256 : p.ps + ((size_t)l * MS + (r0 - MP)) * 256;
	v_mfma_f32_16x16x32_bf16 v[58:61], v[94:97], v[66:69], v[58:61]
	s_add_u32 s30, s30, s26
	v_readlane_b32 s68, v251, 49
	v_mfma_f32_16x16x32_bf16 v[30:33], v[102:105], v[70:73], v[30:33]
	s_addc_u32 s31, s21, s27
	s_lshl_b64 s[26:27], s[0:1], 16
	v_readlane_b32 s80, v251, 61
	v_mfma_f32_16x16x32_bf16 v[42:45], v[90:93], v[70:73], v[42:45]
	v_readlane_b32 s81, v251, 62
	s_add_u32 s26, s80, s26
	s_addc_u32 s27, s81, s27
	v_mfma_f32_16x16x32_bf16 v[34:37], v[98:101], v[70:73], v[34:37]
	v_readlane_b32 s70, v251, 51
	v_readlane_b32 s71, v251, 52
	v_readlane_b32 s41, v254, 53
	v_mfma_f32_16x16x32_bf16 v[2:5], v[98:101], v[86:89], v[2:5]
	v_readlane_b32 s46, v254, 58
	v_readlane_b32 s47, v254, 59
	s_movk_i32 s90, 0x90
	v_mfma_f32_16x16x32_bf16 v[94:97], v[102:105], v[86:89], v[50:53]
	v_mov_b32_e32 v87, v212
	v_readlane_b32 s44, v254, 56
	v_readlane_b32 s45, v254, 57
	v_mfma_f32_16x16x32_bf16 v[70:73], v[122:125], v[110:113], v[38:41]
	v_readlane_b32 s69, v251, 50
	v_readlane_b32 s72, v251, 53
	v_readlane_b32 s73, v251, 54
	v_mfma_f32_16x16x32_bf16 v[38:41], v[122:125], v[114:117], v[22:25]
	v_readlane_b32 s74, v251, 55
	v_readlane_b32 s75, v251, 56
	v_readlane_b32 s76, v251, 57
	v_mfma_f32_16x16x32_bf16 v[22:25], v[82:85], v[114:117], v[14:17]
	v_readlane_b32 s77, v251, 58
	v_readlane_b32 s78, v251, 59
	v_readlane_b32 s79, v251, 60
	v_mfma_f32_16x16x32_bf16 v[14:17], v[118:121], v[74:77], v[10:13]
	v_readlane_b32 s82, v251, 63
	v_readlane_b32 s83, v252, 0
	v_mfma_f32_16x16x32_bf16 v[10:13], v[122:125], v[74:77], v[6:9]
	s_nop 2
	v_lshl_add_u64 v[6:7], v[126:127], 2, s[42:43]
	v_mfma_f32_16x16x32_bf16 v[46:49], v[102:105], v[66:69], v[46:49]
	v_mov_b32_e32 v9, v1
	v_mfma_f32_16x16x32_bf16 v[26:29], v[90:93], v[78:81], v[26:29]
	v_mfma_f32_16x16x32_bf16 v[102:105], v[122:125], v[106:109], v[58:61]
	global_load_dword v86, v[6:7], off
	global_load_dword v122, v[6:7], off offset:64
	global_load_dword v123, v[6:7], off offset:128
	global_load_dword v124, v[6:7], off offset:192
	s_waitcnt vmcnt(0)
	v_fmamk_f32 v141, v124, 0x3a800000, v249
	v_mfma_f32_16x16x32_bf16 v[58:61], v[82:85], v[110:113], v[30:33]
	v_lshlrev_b32_e32 v0, 3, v87
	v_and_b32_e32 v8, 56, v0
	v_lshlrev_b32_e32 v0, 1, v8
	v_ashrrev_i32_e32 v30, 3, v87
	v_ashrrev_i32_e32 v31, 31, v30
	v_lshlrev_b64 v[6:7], 9, v[30:31]
	v_lshl_add_u64 v[6:7], s[26:27], 0, v[6:7]
	v_mfma_f32_16x16x32_bf16 v[62:65], v[90:93], v[66:69], v[62:65]
	v_lshlrev_b32_e32 v8, 2, v8
	v_readfirstlane_b32 s1, v87
	s_lshr_b32 s21, s1, 1
	v_mfma_f32_16x16x32_bf16 v[90:93], v[82:85], v[106:109], v[46:49]
	s_and_b32 s21, s21, 0xfffffc0
	v_cmp_gt_f32_e64 s[42:43], s34, v141
	v_mfma_f32_16x16x32_bf16 v[46:49], v[118:121], v[114:117], v[26:29]
	s_nop 2
	v_lshl_add_u64 v[28:29], v[6:7], 0, v[0:1]
	v_add_u32_e32 v6, 0x100, v87
	v_ashrrev_i32_e32 v88, 3, v6
	v_ashrrev_i32_e32 v89, 31, v88
	v_lshlrev_b64 v[6:7], 9, v[88:89]
	v_lshl_add_u64 v[6:7], s[26:27], 0, v[6:7]
	v_lshl_add_u64 v[26:27], v[6:7], 0, v[0:1]
	v_lshlrev_b64 v[6:7], 10, v[30:31]
	v_lshl_add_u64 v[6:7], s[30:31], 0, v[6:7]
	v_mfma_f32_16x16x32_bf16 v[132:135], v[98:101], v[78:81], v[18:21]
	v_and_b32_e32 v31, 15, v87
	v_mfma_f32_16x16x32_bf16 v[78:81], v[118:121], v[110:113], v[42:45]
	s_nop 2
	v_lshl_add_u64 v[42:43], v[6:7], 0, v[8:9]
	v_add_u32_e32 v6, 0x200, v87
	v_ashrrev_i32_e32 v158, 3, v6
	v_lshlrev_b64 v[6:7], 10, v[88:89]
	v_ashrrev_i32_e32 v159, 31, v158
	v_lshl_add_u64 v[6:7], s[30:31], 0, v[6:7]
	v_lshl_add_u64 v[44:45], v[6:7], 0, v[8:9]
	v_lshlrev_b64 v[6:7], 9, v[158:159]
	v_mfma_f32_16x16x32_bf16 v[54:57], v[98:101], v[66:69], v[54:57]
	v_lshl_add_u64 v[6:7], s[26:27], 0, v[6:7]
	v_lshl_add_u64 v[32:33], v[6:7], 0, v[0:1]
	v_lshlrev_b64 v[6:7], 10, v[158:159]
	v_lshl_add_u64 v[6:7], s[30:31], 0, v[6:7]
	v_lshl_add_u64 v[50:51], v[6:7], 0, v[8:9]
	v_add_u32_e32 v6, 0x300, v87
	v_mfma_f32_16x16x32_bf16 v[18:21], v[118:121], v[106:109], v[62:65]
	v_ashrrev_i32_e32 v166, 3, v6
	v_ashrrev_i32_e32 v167, 31, v166
	v_lshlrev_b64 v[6:7], 10, v[166:167]
	v_mfma_f32_16x16x32_bf16 v[98:101], v[128:131], v[106:109], v[54:57]
	global_load_dwordx4 v[62:65], v[28:29], off
	global_load_dwordx4 v[106:109], v[26:27], off
	v_lshl_add_u64 v[6:7], s[30:31], 0, v[6:7]
	v_lshl_add_u64 v[52:53], v[6:7], 0, v[8:9]
	v_mfma_f32_16x16x32_bf16 v[66:69], v[128:131], v[110:113], v[34:37]
	s_movk_i32 s30, 0x90
	v_mfma_f32_16x16x32_bf16 v[34:37], v[128:131], v[114:117], v[132:135]
	global_load_dwordx4 v[110:113], v[42:43], off offset:16
	global_load_dwordx4 v[114:117], v[42:43], off
	global_load_dwordx4 v[118:121], v[44:45], off offset:16
	global_load_dwordx4 v[132:135], v[44:45], off
	global_load_dwordx4 v[142:145], v[50:51], off offset:16
	global_load_dwordx4 v[146:149], v[50:51], off
	global_load_dwordx4 v[150:153], v[32:33], off
	v_mfma_f32_16x16x32_bf16 v[6:9], v[128:131], v[74:77], v[2:5]
	global_load_dwordx4 v[154:157], v[52:53], off
	global_load_dwordx4 v[162:165], v[52:53], off offset:16
	s_nop 0
	v_lshlrev_b64 v[2:3], 9, v[166:167]
	v_lshl_add_u64 v[2:3], s[26:27], 0, v[2:3]
	v_lshl_add_u64 v[54:55], v[2:3], 0, v[0:1]
	global_load_dwordx4 v[128:131], v[54:55], off
	v_mfma_f32_16x16x32_bf16 v[2:5], v[82:85], v[74:77], v[94:97]
	v_mad_u64_u32 v[56:57], s[26:27], v30, s30, v[0:1]
	v_and_b32_e32 v30, 48, v87
	s_waitcnt vmcnt(0)
	v_cvt_pk_bf16_f32 v76, v110, v111
	v_cvt_pk_bf16_f32 v74, v114, v115
	v_cvt_pk_bf16_f32 v75, v116, v117
	v_cvt_pk_bf16_f32 v77, v112, v113
	ds_write_b128 v56, v[74:77]
	ds_write_b128 v56, v[62:65] offset:36864
	v_cvt_pk_bf16_f32 v74, v132, v133
	v_cvt_pk_bf16_f32 v75, v134, v135
	v_cvt_pk_bf16_f32 v76, v118, v119
	v_cvt_pk_bf16_f32 v77, v120, v121
	v_mad_u64_u32 v[62:63], s[26:27], v88, s30, v[0:1]
	ds_write_b128 v62, v[74:77]
	ds_write_b128 v62, v[106:109] offset:36864
	v_cvt_pk_bf16_f32 v74, v146, v147
	v_cvt_pk_bf16_f32 v75, v148, v149
	v_cvt_pk_bf16_f32 v76, v142, v143
	v_cvt_pk_bf16_f32 v77, v144, v145
	v_mad_u64_u32 v[64:65], s[26:27], v158, s30, v[0:1]
	ds_write_b128 v64, v[74:77]
	ds_write_b128 v64, v[150:153] offset:36864
	v_mad_u64_u32 v[74:75], s[26:27], v166, s30, v[0:1]
	v_and_or_b32 v0, s1, 64, v31
	v_mul_u32_u24_e32 v0, 0x48, v0
	v_cvt_pk_bf16_f32 v82, v154, v155
	v_cvt_pk_bf16_f32 v83, v156, v157
	v_cvt_pk_bf16_f32 v84, v162, v163
	v_cvt_pk_bf16_f32 v85, v164, v165
	v_lshl_add_u32 v0, v0, 1, v30
	ds_write_b128 v74, v[82:85]
	ds_write_b128 v74, v[128:131] offset:36864
	s_waitcnt lgkmcnt(0)
	s_barrier
; template <bool A_F32>
; DI void gemm_core(f32x4 (&acc)[4][4], const void* Ap, int lda, const bf16_t* Bp, int ldb, int K, char* lds) {
;     ...
;   for (int kt = 0; kt < nk; ++kt) {
;     const int buf = kt & 1;
;     if (kt + 1 < nk) gload(kt + 1);
; #pragma unroll
;     for (int ks = 0; ks < 2; ++ks) {
;       bf16x8 af[4], bfr[4];
; #pragma unroll
;       for (int i = 0; i < 4; ++i) {
;         af[i] = *(const bf16x8*)(As + (buf * 128 + wm * 64 + i * 16 + l15) * GLD + ks * 32 + quad * 8);
;         bfr[i] = *(const bf16x8*)(Bs + (buf * 128 + wn * 64 + i * 16 + l15) * GLD + ks * 32 + quad * 8);
;       }
; #pragma unroll
;       for (int mi = 0; mi < 4; ++mi)
; #pragma unroll
;         for (int ni = 0; ni < 4; ++ni) acc[mi][ni] = __builtin_amdgcn_mfma_f32_16x16x32_bf16(bfr[ni], af[mi], acc[mi][ni], 0, 0, 0);
;     }
;     if (kt + 1 < nk) sstore(buf ^ 1, kt + 1);
;     __syncthreads();
	ds_read_b128 v[82:85], v0 offset:36864
	v_or_b32_e32 v31, s21, v31
	v_mad_u64_u32 v[30:31], s[26:27], v31, s30, v[30:31]
	ds_read_b128 v[94:97], v30
	ds_read_b128 v[106:109], v30 offset:64
	ds_read_b128 v[110:113], v0 offset:36928
	ds_read_b128 v[118:121], v0 offset:39168
	ds_read_b128 v[128:131], v0 offset:39232
	ds_read_b128 v[142:145], v0 offset:41472
	ds_read_b128 v[146:149], v0 offset:41536
	ds_read_b128 v[154:157], v0 offset:43776
	ds_read_b128 v[162:165], v0 offset:43840
	ds_read_b128 v[166:169], v30 offset:2304
	ds_read_b128 v[170:173], v30 offset:2368
	ds_read_b128 v[186:189], v30 offset:4608
	ds_read_b128 v[190:193], v30 offset:4672
	ds_read_b128 v[206:209], v30 offset:6912
	ds_read_b128 v[232:235], v30 offset:6976
	s_waitcnt lgkmcnt(14)
	v_mfma_f32_16x16x32_bf16 v[114:117], v[82:85], v[94:97], 0
	s_waitcnt lgkmcnt(11)
	v_mfma_f32_16x16x32_bf16 v[132:135], v[118:121], v[94:97], 0
	s_waitcnt lgkmcnt(9)
	v_mfma_f32_16x16x32_bf16 v[150:153], v[142:145], v[94:97], 0
	s_waitcnt lgkmcnt(7)
	v_mfma_f32_16x16x32_bf16 v[94:97], v[154:157], v[94:97], 0
	s_waitcnt lgkmcnt(5)
	v_mfma_f32_16x16x32_bf16 v[174:177], v[82:85], v[166:169], 0
	v_mfma_f32_16x16x32_bf16 v[178:181], v[118:121], v[166:169], 0
	v_mfma_f32_16x16x32_bf16 v[182:185], v[142:145], v[166:169], 0
	v_mfma_f32_16x16x32_bf16 v[166:169], v[154:157], v[166:169], 0
	s_waitcnt lgkmcnt(3)
	v_mfma_f32_16x16x32_bf16 v[194:197], v[82:85], v[186:189], 0
	v_mfma_f32_16x16x32_bf16 v[198:201], v[118:121], v[186:189], 0
	v_mfma_f32_16x16x32_bf16 v[202:205], v[142:145], v[186:189], 0
	v_mfma_f32_16x16x32_bf16 v[186:189], v[154:157], v[186:189], 0
	s_waitcnt lgkmcnt(1)
	v_mfma_f32_16x16x32_bf16 v[82:85], v[82:85], v[206:209], 0
	v_mfma_f32_16x16x32_bf16 v[118:121], v[118:121], v[206:209], 0
	v_mfma_f32_16x16x32_bf16 v[114:117], v[110:113], v[106:109], v[114:117]
	v_mfma_f32_16x16x32_bf16 v[132:135], v[128:131], v[106:109], v[132:135]
	v_mfma_f32_16x16x32_bf16 v[150:153], v[146:149], v[106:109], v[150:153]
	v_mfma_f32_16x16x32_bf16 v[94:97], v[162:165], v[106:109], v[94:97]
	v_mfma_f32_16x16x32_bf16 v[106:109], v[110:113], v[170:173], v[174:177]
	v_mfma_f32_16x16x32_bf16 v[174:177], v[128:131], v[170:173], v[178:181]
	v_mfma_f32_16x16x32_bf16 v[178:181], v[146:149], v[170:173], v[182:185]
	s_nop 2
	global_load_dwordx4 v[182:185], v[42:43], off offset:256
	v_mfma_f32_16x16x32_bf16 v[142:145], v[142:145], v[206:209], 0
	v_mfma_f32_16x16x32_bf16 v[154:157], v[154:157], v[206:209], 0
	v_mfma_f32_16x16x32_bf16 v[166:169], v[162:165], v[170:173], v[166:169]
	v_mfma_f32_16x16x32_bf16 v[170:173], v[110:113], v[190:193], v[194:197]
	v_mfma_f32_16x16x32_bf16 v[194:197], v[128:131], v[190:193], v[198:201]
	s_nop 2
	global_load_dwordx4 v[198:201], v[42:43], off offset:272
	global_load_dwordx4 v[206:209], v[28:29], off offset:128
	global_load_dwordx4 v[236:239], v[44:45], off offset:256
	global_load_dwordx4 v[240:243], v[44:45], off offset:272
	global_load_dwordx4 v[244:247], v[26:27], off offset:128
	global_load_dwordx4 v[222:225], v[50:51], off offset:256
	v_mfma_f32_16x16x32_bf16 v[202:205], v[146:149], v[190:193], v[202:205]
	v_mfma_f32_16x16x32_bf16 v[186:189], v[162:165], v[190:193], v[186:189]
	global_load_dwordx4 v[190:193], v[50:51], off offset:272
	global_load_dwordx4 v[226:229], v[32:33], off offset:128
	s_waitcnt lgkmcnt(0)
	v_mfma_f32_16x16x32_bf16 v[82:85], v[110:113], v[232:235], v[82:85]
	global_load_dwordx4 v[110:113], v[52:53], off offset:256
	global_load_dwordx4 v[214:217], v[52:53], off offset:272
	s_waitcnt vmcnt(1)
	v_cvt_pk_bf16_f32 v110, v110, v111
	v_mfma_f32_16x16x32_bf16 v[118:121], v[128:131], v[232:235], v[118:121]
	global_load_dwordx4 v[128:131], v[54:55], off offset:128
	v_cvt_pk_bf16_f32 v111, v112, v113
	s_waitcnt vmcnt(1)
	v_cvt_pk_bf16_f32 v112, v214, v215
	v_mfma_f32_16x16x32_bf16 v[142:145], v[146:149], v[232:235], v[142:145]
	v_cvt_pk_bf16_f32 v146, v182, v183
	v_cvt_pk_bf16_f32 v147, v184, v185
	v_cvt_pk_bf16_f32 v148, v198, v199
	v_cvt_pk_bf16_f32 v149, v200, v201
	ds_write_b128 v56, v[146:149] offset:18432
	ds_write_b128 v56, v[206:209] offset:55296
	v_cvt_pk_bf16_f32 v146, v236, v237
	v_cvt_pk_bf16_f32 v147, v238, v239
	v_cvt_pk_bf16_f32 v148, v240, v241
	v_cvt_pk_bf16_f32 v149, v242, v243
	ds_write_b128 v62, v[146:149] offset:18432
	ds_write_b128 v62, v[244:247] offset:55296
	v_cvt_pk_bf16_f32 v146, v222, v223
	v_cvt_pk_bf16_f32 v147, v224, v225
	v_cvt_pk_bf16_f32 v148, v190, v191
	v_cvt_pk_bf16_f32 v149, v192, v193
	v_cvt_pk_bf16_f32 v113, v216, v217
	ds_write_b128 v64, v[146:149] offset:18432
	ds_write_b128 v64, v[226:229] offset:55296
	ds_write_b128 v74, v[110:113] offset:18432
	s_waitcnt vmcnt(0)
	ds_write_b128 v74, v[128:131] offset:55296
	s_waitcnt lgkmcnt(0)
	s_barrier
; template <bool A_F32>
; DI void gemm_core(f32x4 (&acc)[4][4], const void* Ap, int lda, const bf16_t* Bp, int ldb, int K, char* lds) {
;     ...
;   for (int kt = 0; kt < nk; ++kt) {
;     const int buf = kt & 1;
;     if (kt + 1 < nk) gload(kt + 1);
; #pragma unroll
;     for (int ks = 0; ks < 2; ++ks) {
;       bf16x8 af[4], bfr[4];
; #pragma unroll
;       for (int i = 0; i < 4; ++i) {
;         af[i] = *(const bf16x8*)(As + (buf * 128 + wm * 64 + i * 16 + l15) * GLD + ks * 32 + quad * 8);
;         bfr[i] = *(const bf16x8*)(Bs + (buf * 128 + wn * 64 + i * 16 + l15) * GLD + ks * 32 + quad * 8);
;       }
; #pragma unroll
;       for (int mi = 0; mi < 4; ++mi)
; #pragma unroll
;         for (int ni = 0; ni < 4; ++ni) acc[mi][ni] = __builtin_amdgcn_mfma_f32_16x16x32_bf16(bfr[ni], af[mi], acc[mi][ni], 0, 0, 0);
;     }
;     if (kt + 1 < nk) sstore(buf ^ 1, kt + 1);
;     __syncthreads();
	ds_read_b128 v[110:113], v0 offset:55296
	v_mfma_f32_16x16x32_bf16 v[128:131], v[162:165], v[232:235], v[154:157]
	ds_read_b128 v[146:149], v30 offset:18432
	s_nop 1
	ds_read_b128 v[154:157], v30 offset:18496
	ds_read_b128 v[162:165], v0 offset:55360
	ds_read_b128 v[182:185], v0 offset:57600
	ds_read_b128 v[190:193], v0 offset:57664
	ds_read_b128 v[198:201], v0 offset:59904
	ds_read_b128 v[206:209], v0 offset:59968
	ds_read_b128 v[214:217], v0 offset:62208
	ds_read_b128 v[222:225], v0 offset:62272
	s_waitcnt lgkmcnt(8)
	v_mfma_f32_16x16x32_bf16 v[114:117], v[110:113], v[146:149], v[114:117]
	s_waitcnt lgkmcnt(5)
	v_mfma_f32_16x16x32_bf16 v[132:135], v[182:185], v[146:149], v[132:135]
	s_waitcnt lgkmcnt(3)
	v_mfma_f32_16x16x32_bf16 v[150:153], v[198:201], v[146:149], v[150:153]
	s_waitcnt lgkmcnt(1)
	v_mfma_f32_16x16x32_bf16 v[94:97], v[214:217], v[146:149], v[94:97]
	ds_read_b128 v[146:149], v30 offset:20736
	ds_read_b128 v[226:229], v30 offset:20800
	s_waitcnt lgkmcnt(1)
	v_mfma_f32_16x16x32_bf16 v[106:109], v[110:113], v[146:149], v[106:109]
	v_mfma_f32_16x16x32_bf16 v[174:177], v[182:185], v[146:149], v[174:177]
	v_mfma_f32_16x16x32_bf16 v[178:181], v[198:201], v[146:149], v[178:181]
	v_mfma_f32_16x16x32_bf16 v[146:149], v[214:217], v[146:149], v[166:169]
	s_nop 2
	ds_read_b128 v[166:169], v30 offset:23040
	ds_read_b128 v[232:235], v30 offset:23104
	s_waitcnt lgkmcnt(1)
	v_mfma_f32_16x16x32_bf16 v[170:173], v[110:113], v[166:169], v[170:173]
	v_mfma_f32_16x16x32_bf16 v[194:197], v[182:185], v[166:169], v[194:197]
	v_mfma_f32_16x16x32_bf16 v[202:205], v[198:201], v[166:169], v[202:205]
	v_mfma_f32_16x16x32_bf16 v[166:169], v[214:217], v[166:169], v[186:189]
	s_nop 2
	ds_read_b128 v[186:189], v30 offset:25344
	ds_read_b128 v[236:239], v30 offset:25408
	s_waitcnt lgkmcnt(1)
	v_mfma_f32_16x16x32_bf16 v[82:85], v[110:113], v[186:189], v[82:85]
	v_mfma_f32_16x16x32_bf16 v[110:113], v[182:185], v[186:189], v[118:121]
	v_mfma_f32_16x16x32_bf16 v[118:121], v[198:201], v[186:189], v[142:145]
	v_mfma_f32_16x16x32_bf16 v[142:145], v[206:209], v[154:157], v[150:153]
	v_mfma_f32_16x16x32_bf16 v[150:153], v[190:193], v[226:229], v[174:177]
	s_nop 2
	global_load_dwordx4 v[174:177], v[42:43], off offset:512
	v_mfma_f32_16x16x32_bf16 v[128:131], v[214:217], v[186:189], v[128:131]
	s_waitcnt vmcnt(0)
	v_cvt_pk_bf16_f32 v174, v174, v175
	v_mfma_f32_16x16x32_bf16 v[114:117], v[162:165], v[154:157], v[114:117]
	v_cvt_pk_bf16_f32 v175, v176, v177
	v_mfma_f32_16x16x32_bf16 v[132:135], v[190:193], v[154:157], v[132:135]
	v_mfma_f32_16x16x32_bf16 v[94:97], v[222:225], v[154:157], v[94:97]
	v_mfma_f32_16x16x32_bf16 v[154:157], v[206:209], v[226:229], v[178:181]
	v_mfma_f32_16x16x32_bf16 v[178:181], v[190:193], v[232:235], v[194:197]
	global_load_dwordx4 v[182:185], v[42:43], off offset:528
	global_load_dwordx4 v[186:189], v[28:29], off offset:256
	s_nop 0
	global_load_dwordx4 v[194:197], v[44:45], off offset:512
	s_waitcnt vmcnt(2)
	v_cvt_pk_bf16_f32 v176, v182, v183
	v_mfma_f32_16x16x32_bf16 v[106:109], v[162:165], v[226:229], v[106:109]
	v_cvt_pk_bf16_f32 v177, v184, v185
	v_mfma_f32_16x16x32_bf16 v[146:149], v[222:225], v[226:229], v[146:149]
	v_mfma_f32_16x16x32_bf16 v[170:173], v[162:165], v[232:235], v[170:173]
	v_mfma_f32_16x16x32_bf16 v[198:201], v[206:209], v[232:235], v[202:205]
	s_nop 2
	global_load_dwordx4 v[202:205], v[44:45], off offset:528
	global_load_dwordx4 v[214:217], v[26:27], off offset:256
	global_load_dwordx4 v[226:229], v[50:51], off offset:512
	v_mfma_f32_16x16x32_bf16 v[166:169], v[222:225], v[232:235], v[166:169]
	global_load_dwordx4 v[232:235], v[50:51], off offset:528
	global_load_dwordx4 v[240:243], v[32:33], off offset:256
	s_waitcnt lgkmcnt(0)
	v_mfma_f32_16x16x32_bf16 v[82:85], v[162:165], v[236:239], v[82:85]
	global_load_dwordx4 v[162:165], v[52:53], off offset:512
	global_load_dwordx4 v[244:247], v[52:53], off offset:528
	s_waitcnt vmcnt(1)
	v_cvt_pk_bf16_f32 v162, v162, v163
	v_mfma_f32_16x16x32_bf16 v[110:113], v[190:193], v[236:239], v[110:113]
	global_load_dwordx4 v[190:193], v[54:55], off offset:256
	ds_write_b128 v56, v[174:177]
	ds_write_b128 v56, v[186:189] offset:36864
	v_cvt_pk_bf16_f32 v174, v194, v195
	v_cvt_pk_bf16_f32 v175, v196, v197
	v_cvt_pk_bf16_f32 v176, v202, v203
	v_cvt_pk_bf16_f32 v177, v204, v205
	ds_write_b128 v62, v[174:177]
	ds_write_b128 v62, v[214:217] offset:36864
	v_cvt_pk_bf16_f32 v174, v226, v227
	v_cvt_pk_bf16_f32 v175, v228, v229
	v_cvt_pk_bf16_f32 v176, v232, v233
	v_cvt_pk_bf16_f32 v177, v234, v235
	v_cvt_pk_bf16_f32 v163, v164, v165
	s_waitcnt vmcnt(1)
	v_cvt_pk_bf16_f32 v164, v244, v245
	v_cvt_pk_bf16_f32 v165, v246, v247
	ds_write_b128 v64, v[174:177]
	ds_write_b128 v64, v[240:243] offset:36864
	ds_write_b128 v74, v[162:165]
	s_waitcnt vmcnt(0)
	ds_write_b128 v74, v[190:193] offset:36864
	s_waitcnt lgkmcnt(0)
	s_barrier
; template <bool A_F32>
; DI void gemm_core(f32x4 (&acc)[4][4], const void* Ap, int lda, const bf16_t* Bp, int ldb, int K, char* lds) {
;     ...
;   for (int kt = 0; kt < nk; ++kt) {
;     const int buf = kt & 1;
;     if (kt + 1 < nk) gload(kt + 1);
; #pragma unroll
;     for (int ks = 0; ks < 2; ++ks) {
;       bf16x8 af[4], bfr[4];
; #pragma unroll
;       for (int i = 0; i < 4; ++i) {
;         af[i] = *(const bf16x8*)(As + (buf * 128 + wm * 64 + i * 16 + l15) * GLD + ks * 32 + quad * 8);
;         bfr[i] = *(const bf16x8*)(Bs + (buf * 128 + wn * 64 + i * 16 + l15) * GLD + ks * 32 + quad * 8);
;       }
; #pragma unroll
;       for (int mi = 0; mi < 4; ++mi)
; #pragma unroll
;         for (int ni = 0; ni < 4; ++ni) acc[mi][ni] = __builtin_amdgcn_mfma_f32_16x16x32_bf16(bfr[ni], af[mi], acc[mi][ni], 0, 0, 0);
;     }
;     if (kt + 1 < nk) sstore(buf ^ 1, kt + 1);
;     __syncthreads();
	ds_read_b128 v[162:165], v0 offset:36864
	v_mfma_f32_16x16x32_bf16 v[118:121], v[206:209], v[236:239], v[118:121]
	ds_read_b128 v[174:177], v30
	ds_read_b128 v[182:185], v30 offset:64
	ds_read_b128 v[186:189], v0 offset:36928
	ds_read_b128 v[190:193], v0 offset:39168
	ds_read_b128 v[194:197], v0 offset:39232
	ds_read_b128 v[202:205], v0 offset:41472
	ds_read_b128 v[206:209], v0 offset:41536
	v_mfma_f32_16x16x32_bf16 v[128:131], v[222:225], v[236:239], v[128:131]
	ds_read_b128 v[214:217], v0 offset:43776
	ds_read_b128 v[222:225], v0 offset:43840
	s_waitcnt lgkmcnt(8)
	v_mfma_f32_16x16x32_bf16 v[114:117], v[162:165], v[174:177], v[114:117]
	s_waitcnt lgkmcnt(5)
	v_mfma_f32_16x16x32_bf16 v[132:135], v[190:193], v[174:177], v[132:135]
	s_waitcnt lgkmcnt(3)
	v_mfma_f32_16x16x32_bf16 v[142:145], v[202:205], v[174:177], v[142:145]
	s_waitcnt lgkmcnt(1)
	v_mfma_f32_16x16x32_bf16 v[94:97], v[214:217], v[174:177], v[94:97]
	ds_read_b128 v[174:177], v30 offset:2304
	ds_read_b128 v[226:229], v30 offset:2368
	s_waitcnt lgkmcnt(1)
	v_mfma_f32_16x16x32_bf16 v[106:109], v[162:165], v[174:177], v[106:109]
	v_mfma_f32_16x16x32_bf16 v[150:153], v[190:193], v[174:177], v[150:153]
	v_mfma_f32_16x16x32_bf16 v[154:157], v[202:205], v[174:177], v[154:157]
	v_mfma_f32_16x16x32_bf16 v[146:149], v[214:217], v[174:177], v[146:149]
	ds_read_b128 v[174:177], v30 offset:4608
	ds_read_b128 v[232:235], v30 offset:4672
	s_waitcnt lgkmcnt(1)
	v_mfma_f32_16x16x32_bf16 v[170:173], v[162:165], v[174:177], v[170:173]
	v_mfma_f32_16x16x32_bf16 v[178:181], v[190:193], v[174:177], v[178:181]
	v_mfma_f32_16x16x32_bf16 v[198:201], v[202:205], v[174:177], v[198:201]
	v_mfma_f32_16x16x32_bf16 v[166:169], v[214:217], v[174:177], v[166:169]
	ds_read_b128 v[174:177], v30 offset:6912
	ds_read_b128 v[236:239], v30 offset:6976
	s_waitcnt lgkmcnt(1)
	v_mfma_f32_16x16x32_bf16 v[82:85], v[162:165], v[174:177], v[82:85]
	v_mfma_f32_16x16x32_bf16 v[162:165], v[186:189], v[232:235], v[170:173]
	s_nop 2
	global_load_dwordx4 v[170:173], v[42:43], off offset:768
	v_mfma_f32_16x16x32_bf16 v[110:113], v[190:193], v[174:177], v[110:113]
	s_waitcnt vmcnt(0)
	v_cvt_pk_bf16_f32 v170, v170, v171
	v_mfma_f32_16x16x32_bf16 v[118:121], v[202:205], v[174:177], v[118:121]
	v_cvt_pk_bf16_f32 v171, v172, v173
	v_mfma_f32_16x16x32_bf16 v[128:131], v[214:217], v[174:177], v[128:131]
	v_mfma_f32_16x16x32_bf16 v[114:117], v[186:189], v[182:185], v[114:117]
	v_mfma_f32_16x16x32_bf16 v[132:135], v[194:197], v[182:185], v[132:135]
	v_mfma_f32_16x16x32_bf16 v[142:145], v[206:209], v[182:185], v[142:145]
	v_mfma_f32_16x16x32_bf16 v[94:97], v[222:225], v[182:185], v[94:97]
	v_mfma_f32_16x16x32_bf16 v[174:177], v[194:197], v[232:235], v[178:181]
	s_nop 2
	global_load_dwordx4 v[178:181], v[42:43], off offset:784
	global_load_dwordx4 v[182:185], v[28:29], off offset:384
	global_load_dwordx4 v[190:193], v[44:45], off offset:768
	s_nop 0
	global_load_dwordx4 v[42:45], v[44:45], off offset:784
	s_nop 0
	global_load_dwordx4 v[26:29], v[26:27], off offset:384
	s_nop 0
	global_load_dwordx4 v[202:205], v[50:51], off offset:768
	s_waitcnt vmcnt(5)
	v_cvt_pk_bf16_f32 v172, v178, v179
	v_mfma_f32_16x16x32_bf16 v[106:109], v[186:189], v[226:229], v[106:109]
	v_cvt_pk_bf16_f32 v173, v180, v181
	s_waitcnt vmcnt(2)
	v_cvt_pk_bf16_f32 v57, v44, v45
	v_mfma_f32_16x16x32_bf16 v[150:153], v[194:197], v[226:229], v[150:153]
	v_mfma_f32_16x16x32_bf16 v[154:157], v[206:209], v[226:229], v[154:157]
	v_mfma_f32_16x16x32_bf16 v[146:149], v[222:225], v[226:229], v[146:149]
	global_load_dwordx4 v[214:217], v[50:51], off offset:784
	global_load_dwordx4 v[226:229], v[32:33], off offset:384
	s_waitcnt lgkmcnt(0)
	v_mfma_f32_16x16x32_bf16 v[82:85], v[186:189], v[236:239], v[82:85]
	global_load_dwordx4 v[186:189], v[52:53], off offset:768
	s_nop 0
	global_load_dwordx4 v[50:53], v[52:53], off offset:784
	v_mfma_f32_16x16x32_bf16 v[110:113], v[194:197], v[236:239], v[110:113]
	global_load_dwordx4 v[194:197], v[54:55], off offset:384
	ds_write_b128 v56, v[170:173] offset:18432
	ds_write_b128 v56, v[182:185] offset:55296
	v_cvt_pk_bf16_f32 v54, v190, v191
	v_cvt_pk_bf16_f32 v55, v192, v193
	v_cvt_pk_bf16_f32 v56, v42, v43
	ds_write_b128 v62, v[54:57] offset:18432
	s_waitcnt vmcnt(6)
	ds_write_b128 v62, v[26:29] offset:55296
	s_waitcnt vmcnt(5)
	v_cvt_pk_bf16_f32 v26, v202, v203
	v_cvt_pk_bf16_f32 v27, v204, v205
	v_mfma_f32_16x16x32_bf16 v[42:45], v[222:225], v[236:239], v[128:131]
	s_waitcnt vmcnt(4)
	v_cvt_pk_bf16_f32 v28, v214, v215
	v_cvt_pk_bf16_f32 v29, v216, v217
	ds_write_b128 v64, v[26:29] offset:18432
	s_waitcnt vmcnt(3)
	ds_write_b128 v64, v[226:229] offset:55296
	v_mfma_f32_16x16x32_bf16 v[198:201], v[206:209], v[232:235], v[198:201]
	s_waitcnt vmcnt(2)
	v_cvt_pk_bf16_f32 v26, v186, v187
	v_cvt_pk_bf16_f32 v27, v188, v189
	s_waitcnt vmcnt(1)
	v_cvt_pk_bf16_f32 v28, v50, v51
	v_cvt_pk_bf16_f32 v29, v52, v53
	ds_write_b128 v74, v[26:29] offset:18432
	s_waitcnt vmcnt(0)
	ds_write_b128 v74, v[194:197] offset:55296
	s_waitcnt lgkmcnt(0)
	s_barrier
; template <bool A_F32>
; DI void gemm_core(f32x4 (&acc)[4][4], const void* Ap, int lda, const bf16_t* Bp, int ldb, int K, char* lds) {
;     ...
;   for (int kt = 0; kt < nk; ++kt) {
;     const int buf = kt & 1;
;     if (kt + 1 < nk) gload(kt + 1);
; #pragma unroll
;     for (int ks = 0; ks < 2; ++ks) {
;       bf16x8 af[4], bfr[4];
; #pragma unroll
;       for (int i = 0; i < 4; ++i) {
;         af[i] = *(const bf16x8*)(As + (buf * 128 + wm * 64 + i * 16 + l15) * GLD + ks * 32 + quad * 8);
;         bfr[i] = *(const bf16x8*)(Bs + (buf * 128 + wn * 64 + i * 16 + l15) * GLD + ks * 32 + quad * 8);
;       }
; #pragma unroll
;       for (int mi = 0; mi < 4; ++mi)
; #pragma unroll
;         for (int ni = 0; ni < 4; ++ni) acc[mi][ni] = __builtin_amdgcn_mfma_f32_16x16x32_bf16(bfr[ni], af[mi], acc[mi][ni], 0, 0, 0);
;     }
;     if (kt + 1 < nk) sstore(buf ^ 1, kt + 1);
;     __syncthreads();
; DI void phase_ple(const Params& p, int l, char* lds) {
;     ...
;       const float rs = rsqrtf(p.ss2[mt * 128 + wm * 64 + mi * 16 + l15] * (1.0f / 1024.0f) + 1e-6f);
; #pragma unroll
;       for (int ni = 0; ni < 4; ++ni) { const f32x4 v = a1[mi][ni] * rs; pk[mi][ni][0] = pk2(sigmoidf_(v[0]), sigmoidf_(v[1])); pk[mi][ni][1] = pk2(sigmoidf_(v[2]), sigmoidf_(v[3])); }
;     }
;     zero_acc(a1);
;     const int r0 = mt * 128;
;     const float* pa = r0 < MP ? p.pp + ((size_t)l * MP + r0) * 256 : p.ps + ((size_t)l * MS + (r0 - MP)) * 256;
;     gemm_core<true>(a1, pa, 256, p.wt_ple + (size_t)nt * 128 * 256, 256, 256, lds);
; #pragma unroll
;     for (int mi = 0; mi < 4; ++mi) {
;       const int R = mt * 128 + wm * 64 + mi * 16 + l15;
;       float sq = 0.f;
; #pragma unroll
;       for (int ni = 0; ni < 4; ++ni) {
;         const int c = nt * 128 + wn * 64 + ni * 16 + quad * 4;
;         float* xo = p.out + (size_t)R * DM + c;
;         const f32x4 xv = *(const f32x4*)xo; const f32x4 e = a1[mi][ni]; const u32x2 g = pk[mi][ni];
;         f32x4 o;
;         o[0] = xv[0] + e[0] * bf_lo(g[0]); o[1] = xv[1] + e[1] * bf_hi(g[0]);
;         o[2] = xv[2] + e[2] * bf_lo(g[1]); o[3] = xv[3] + e[3] * bf_hi(g[1]);
;         *(f32x4*)xo = o;
;         if (l + 1 < NL) {
;           const f32x4 gn = *(const f32x4*)(p.norm_g + (l + 1) * DM + c);
;           u32x2 hv; hv[0] = pk2(o[0] * gn[0], o[1] * gn[1]); hv[1] = pk2(o[2] * gn[2], o[3] * gn[3]);
;           *(u32x2*)(p.hn + (size_t)R * DM + c) = hv;
	ds_read_b128 v[26:29], v0 offset:55296
	ds_read_b128 v[50:53], v30 offset:18432
	ds_read_b128 v[54:57], v30 offset:18496
	ds_read_b128 v[170:173], v0 offset:55360
	ds_read_b128 v[74:77], v0 offset:57600
	ds_read_b128 v[178:181], v0 offset:57664
	s_waitcnt lgkmcnt(4)
	v_mfma_f32_16x16x32_bf16 v[62:65], v[26:29], v[50:53], v[114:117]
	v_lshl_or_b32 v128, s0, 7, v140
	v_ashrrev_i32_e32 v129, 31, v128
	s_waitcnt lgkmcnt(1)
	v_mfma_f32_16x16x32_bf16 v[114:117], v[74:77], v[50:53], v[132:135]
	s_nop 2
	ds_read_b128 v[130:133], v0 offset:59904
	ds_read_b128 v[182:185], v0 offset:59968
	ds_read_b128 v[186:189], v0 offset:62208
	ds_read_b128 v[190:193], v0 offset:62272
	v_fmamk_f32 v0, v86, 0x3a800000, v249
	s_waitcnt lgkmcnt(3)
	v_mfma_f32_16x16x32_bf16 v[142:145], v[130:133], v[50:53], v[142:145]
	v_cmp_gt_f32_e32 vcc, s34, v0
	s_waitcnt lgkmcnt(1)
	v_mfma_f32_16x16x32_bf16 v[50:53], v[186:189], v[50:53], v[94:97]
	s_nop 2
	ds_read_b128 v[94:97], v30 offset:20736
	ds_read_b128 v[194:197], v30 offset:20800
	v_mfma_f32_16x16x32_bf16 v[166:169], v[222:225], v[232:235], v[166:169]
	s_waitcnt lgkmcnt(1)
	v_mfma_f32_16x16x32_bf16 v[106:109], v[26:29], v[94:97], v[106:109]
	v_mfma_f32_16x16x32_bf16 v[150:153], v[74:77], v[94:97], v[150:153]
	v_mfma_f32_16x16x32_bf16 v[154:157], v[130:133], v[94:97], v[154:157]
	v_mfma_f32_16x16x32_bf16 v[146:149], v[186:189], v[94:97], v[146:149]
	ds_read_b128 v[94:97], v30 offset:23040
	ds_read_b128 v[202:205], v30 offset:23104
	v_mfma_f32_16x16x32_bf16 v[118:121], v[206:209], v[236:239], v[118:121]
	s_waitcnt lgkmcnt(1)
	v_mfma_f32_16x16x32_bf16 v[162:165], v[26:29], v[94:97], v[162:165]
	v_mfma_f32_16x16x32_bf16 v[174:177], v[74:77], v[94:97], v[174:177]
	v_mfma_f32_16x16x32_bf16 v[198:201], v[130:133], v[94:97], v[198:201]
	v_mfma_f32_16x16x32_bf16 v[166:169], v[186:189], v[94:97], v[166:169]
	ds_read_b128 v[94:97], v30 offset:25344
	ds_read_b128 v[206:209], v30 offset:25408
	s_waitcnt lgkmcnt(0)
	s_barrier
	v_mfma_f32_16x16x32_bf16 v[30:33], v[74:77], v[94:97], v[110:113]
	v_lshlrev_b64 v[74:75], 12, v[126:127]
	v_lshl_add_u64 v[74:75], s[70:71], 0, v[74:75]
	v_mfma_f32_16x16x32_bf16 v[214:217], v[130:133], v[94:97], v[118:121]
	v_lshl_add_u64 v[132:133], v[128:129], 2, v[74:75]
	global_load_dwordx4 v[222:225], v[132:133], off
	v_lshl_add_u64 v[130:131], v[128:129], 2, s[24:25]
	v_mfma_f32_16x16x32_bf16 v[186:189], v[186:189], v[94:97], v[42:45]
	s_nop 2
	v_mul_f32_e32 v42, 0x4b800000, v0
	v_cndmask_b32_e32 v0, v0, v42, vcc
	v_rsq_f32_e32 v0, v0
	v_mfma_f32_16x16x32_bf16 v[226:229], v[170:173], v[54:57], v[62:65]
	v_mul_f32_e32 v42, 0x45800000, v0
	v_cndmask_b32_e32 v0, v0, v42, vcc
	v_pk_mul_f32 v[18:19], v[18:19], v[0:1] op_sel_hi:[1,0]
	v_pk_mul_f32 v[20:21], v[20:21], v[0:1] op_sel_hi:[1,0]
	v_mul_f32_e32 v18, 0xbfb8aa3b, v18
	v_mul_f32_e32 v19, 0xbfb8aa3b, v19
	v_exp_f32_e32 v18, v18
	v_exp_f32_e32 v19, v19
	v_mul_f32_e32 v20, 0xbfb8aa3b, v20
	v_mul_f32_e32 v21, 0xbfb8aa3b, v21
	v_exp_f32_e32 v20, v20
	v_exp_f32_e32 v21, v21
	v_add_f32_e32 v18, 1.0, v18
	v_add_f32_e32 v19, 1.0, v19
	v_rcp_f32_e32 v18, v18
	v_rcp_f32_e32 v19, v19
	v_add_f32_e32 v20, 1.0, v20
	v_add_f32_e32 v21, 1.0, v21
	v_rcp_f32_e32 v20, v20
	v_rcp_f32_e32 v21, v21
	v_mfma_f32_16x16x32_bf16 v[26:29], v[26:29], v[94:97], v[82:85]
	v_cvt_pk_bf16_f32 v42, v18, v19
	v_lshlrev_b64 v[18:19], 10, v[126:127]
	v_cvt_pk_bf16_f32 v125, v20, v21
	v_lshlrev_b32_e32 v20, 16, v42
	v_and_b32_e32 v21, 0xffff0000, v42
	v_mfma_f32_16x16x32_bf16 v[118:121], v[178:181], v[54:57], v[114:117]
	v_lshl_add_u64 v[134:135], v[18:19], 1, s[8:9]
	s_andn2_b64 vcc, exec, s[2:3]
	v_mfma_f32_16x16x32_bf16 v[114:117], v[182:185], v[54:57], v[142:145]
	s_nop 2
	v_fmamk_f32 v143, v122, 0x3a800000, v249
	v_fmamk_f32 v142, v123, 0x3a800000, v249
	v_mfma_f32_16x16x32_bf16 v[110:113], v[190:193], v[54:57], v[50:53]
	v_cmp_gt_f32_e64 s[46:47], s34, v143
	v_cmp_gt_f32_e64 s[0:1], s34, v142
	v_mov_b32_e32 v144, 0
	v_mfma_f32_16x16x32_bf16 v[106:109], v[170:173], v[194:197], v[106:109]
	s_waitcnt vmcnt(0)
	v_pk_fma_f32 v[122:123], v[226:227], v[20:21], v[222:223]
	v_lshlrev_b32_e32 v20, 16, v125
	v_and_b32_e32 v21, 0xffff0000, v125
	v_pk_fma_f32 v[124:125], v[228:229], v[20:21], v[224:225]
	v_cndmask_b32_e64 v20, 0, 1, s[2:3]
	v_mfma_f32_16x16x32_bf16 v[94:97], v[178:181], v[194:197], v[150:153]
	v_cmp_ne_u32_e64 s[40:41], 1, v20
	global_store_dwordx4 v[132:133], v[122:125], off
	v_mfma_f32_16x16x32_bf16 v[86:89], v[182:185], v[194:197], v[154:157]
	v_mfma_f32_16x16x32_bf16 v[82:85], v[190:193], v[194:197], v[146:149]
	v_mfma_f32_16x16x32_bf16 v[74:77], v[170:173], v[202:205], v[162:165]
	v_mfma_f32_16x16x32_bf16 v[62:65], v[178:181], v[202:205], v[174:177]
	v_mfma_f32_16x16x32_bf16 v[54:57], v[182:185], v[202:205], v[198:201]
	v_mfma_f32_16x16x32_bf16 v[50:53], v[190:193], v[202:205], v[166:169]
	v_mfma_f32_16x16x32_bf16 v[42:45], v[170:173], v[206:209], v[26:29]
	v_mfma_f32_16x16x32_bf16 v[30:33], v[178:181], v[206:209], v[30:33]
	v_mfma_f32_16x16x32_bf16 v[26:29], v[182:185], v[206:209], v[214:217]
	v_mfma_f32_16x16x32_bf16 v[18:21], v[190:193], v[206:209], v[186:189]
	s_cbranch_vccnz .LBB0_906
	global_load_dwordx4 v[144:147], v[130:131], off
	s_waitcnt vmcnt(0)
	v_pk_mul_f32 v[144:145], v[122:123], v[144:145]
	v_pk_mul_f32 v[122:123], v[122:123], v[122:123]
	v_pk_mul_f32 v[146:147], v[124:125], v[146:147]
	v_pk_mul_f32 v[124:125], v[124:125], v[124:125]
	v_add_f32_e32 v122, v122, v123
	v_cvt_pk_bf16_f32 v144, v144, v145
	v_cvt_pk_bf16_f32 v145, v146, v147
	v_lshl_add_u64 v[146:147], v[128:129], 1, v[134:135]
	v_add_f32_e32 v122, v124, v122
	global_store_dwordx2 v[146:147], v[144:145], off
	v_add_f32_e32 v144, v125, v122
